# scan MFMA stage: all LDS reads hoisted to stage top, QDT fragments reused, state decay in score-MFMA shadow
# baseline (speedup 1.0000x reference)
.LBB0_418:
	s_waitcnt lgkmcnt(0)
	s_barrier
	ds_read_b64_tr_b16 v[104:105], v68 offset:8192
	ds_read_b64_tr_b16 v[106:107], v68 offset:8704
	ds_read_b64_tr_b16 v[108:109], v68
	ds_read_b64_tr_b16 v[110:111], v68 offset:512
	ds_read_b64_tr_b16 v[112:113], v68 offset:9216
	ds_read_b64_tr_b16 v[114:115], v68 offset:9728
	ds_read_b64_tr_b16 v[116:117], v68 offset:1024
	ds_read_b64_tr_b16 v[118:119], v68 offset:1536
	v_lshlrev_b32_e32 v192, 1, v52
	v_add3_u32 v103, s25, v64, v192
	v_add_u32_e32 v193, 0x6800, v103
	ds_read2_b64 v[120:123], v193 offset1:2
	ds_read2_b64 v[124:127], v193 offset0:4 offset1:6
	ds_read_b128 v[128:131], v71 offset:36864
	ds_read_b128 v[132:135], v71 offset:36896
	ds_read_b128 v[136:139], v71 offset:36928
	ds_read_b128 v[140:143], v71 offset:36960
	v_add_u32_e32 v194, v103, v65
	ds_read_b128 v[144:147], v66 offset:16384
	s_add_u32 s0, s0, 0x10000
	s_addc_u32 s1, s1, 0
	s_cmp_lg_u32 s0, 0x800000
	v_cvt_pk_bf16_f32 v184, v2, v3
	v_cvt_pk_bf16_f32 v185, v4, v5
	v_cvt_pk_bf16_f32 v186, v6, v7
	v_cvt_pk_bf16_f32 v187, v8, v9
	v_cvt_pk_bf16_f32 v188, v10, v11
	v_cvt_pk_bf16_f32 v189, v12, v13
	v_cvt_pk_bf16_f32 v190, v14, v15
	v_cvt_pk_bf16_f32 v191, v16, v17
	s_waitcnt lgkmcnt(11)
	v_mfma_f32_32x32x16_bf16 v[160:175], v[104:107], v[108:111], 0
	ds_read_b128 v[148:151], v66 offset:16416
	ds_read_b128 v[152:155], v194 offset:26624
	ds_read_b128 v[156:159], v194 offset:26656
	s_mov_b32 s8, s24
	s_waitcnt lgkmcnt(10)
	v_mfma_f32_32x32x16_bf16 v[160:175], v[112:115], v[116:119], v[160:175]
	s_waitcnt lgkmcnt(4)
	v_pk_mul_f32 v[2:3], v[2:3], v[128:129]
	v_pk_mul_f32 v[4:5], v[4:5], v[130:131]
	v_pk_mul_f32 v[6:7], v[6:7], v[132:133]
	v_pk_mul_f32 v[8:9], v[8:9], v[134:135]
	v_pk_mul_f32 v[10:11], v[10:11], v[136:137]
	v_pk_mul_f32 v[12:13], v[12:13], v[138:139]
	v_pk_mul_f32 v[14:15], v[14:15], v[140:141]
	v_pk_mul_f32 v[16:17], v[16:17], v[142:143]
	s_nop 3
	v_cndmask_b32_e64 v195, v160, 0, s[46:47]
	v_cndmask_b32_e64 v160, v195, v160, s[48:49]
	v_cndmask_b32_e64 v161, 0, v161, s[48:49]
	v_cndmask_b32_e64 v162, v162, 0, s[50:51]
	v_cndmask_b32_e64 v163, v163, 0, s[52:53]
	v_cndmask_b32_e64 v164, v164, 0, s[54:55]
	v_cndmask_b32_e64 v165, v165, 0, s[56:57]
	v_cndmask_b32_e64 v166, v166, 0, s[58:59]
	v_cndmask_b32_e64 v167, v167, 0, s[60:61]
	v_cndmask_b32_e64 v168, v168, 0, s[62:63]
	v_cndmask_b32_e64 v169, v169, 0, s[64:65]
	v_cndmask_b32_e64 v170, v170, 0, s[66:67]
	v_cndmask_b32_e64 v171, v171, 0, s[68:69]
	v_cndmask_b32_e64 v172, v172, 0, s[70:71]
	v_cndmask_b32_e64 v173, v173, 0, s[72:73]
	v_cndmask_b32_e64 v174, v174, 0, s[74:75]
	v_cndmask_b32_e64 v175, v175, 0, s[76:77]
	v_cvt_pk_bf16_f32 v176, v160, v161
	v_cvt_pk_bf16_f32 v177, v162, v163
	v_cvt_pk_bf16_f32 v178, v164, v165
	v_cvt_pk_bf16_f32 v179, v166, v167
	v_cvt_pk_bf16_f32 v180, v168, v169
	v_cvt_pk_bf16_f32 v181, v170, v171
	v_cvt_pk_bf16_f32 v182, v172, v173
	v_cvt_pk_bf16_f32 v183, v174, v175
	v_mfma_f32_32x32x16_bf16 v[18:33], v[120:123], v[176:179], 0
	v_mfma_f32_32x32x16_bf16 v[18:33], v[184:187], v[108:111], v[18:33]
	v_mfma_f32_32x32x16_bf16 v[18:33], v[124:127], v[180:183], v[18:33]
	v_mfma_f32_32x32x16_bf16 v[18:33], v[188:191], v[116:119], v[18:33]
	s_waitcnt lgkmcnt(1)
	v_mfma_f32_32x32x16_bf16 v[2:17], v[144:147], v[152:155], v[2:17]
	s_waitcnt lgkmcnt(0)
	v_mfma_f32_32x32x16_bf16 v[2:17], v[148:151], v[156:159], v[2:17]
	s_nop 7
	v_cvt_pk_bf16_f32 v18, v18, v19
	ds_write_b32 v75, v18 offset:37376
	v_cvt_pk_bf16_f32 v18, v20, v21
	ds_write_b32 v76, v18 offset:37376
	v_cvt_pk_bf16_f32 v18, v22, v23
	ds_write_b32 v77, v18 offset:37376
	v_cvt_pk_bf16_f32 v18, v24, v25
	ds_write_b32 v78, v18 offset:37376
	v_cvt_pk_bf16_f32 v18, v26, v27
	ds_write_b32 v79, v18 offset:37376
	v_cvt_pk_bf16_f32 v18, v28, v29
	ds_write_b32 v80, v18 offset:37376
	v_cvt_pk_bf16_f32 v18, v30, v31
	ds_write_b32 v81, v18 offset:37376
	v_cvt_pk_bf16_f32 v18, v32, v33
	ds_write_b32 v82, v18 offset:37376
	s_waitcnt lgkmcnt(0)
	s_barrier
	s_cbranch_scc0 .LBB0_414
